# panel-counter waits: only wave 0 polls, then a workgroup barrier (less polling traffic); otherwise v089
# speedup vs baseline: 1.0026x; 1.0026x over previous
; #define PG8_STAGE(bufoff, gbase, voff) do { _Pragma("unroll") for (int _i = 0; _i < 2; ++_i) \
;         __builtin_amdgcn_global_load_lds((const unsigned*)((const char*)(gbase) + (voff)[_i]), (PG8_LAS unsigned*)(lds + (bufoff) + ldsw + _i * 8192), 16, 0, 0); } while (0)
; #define PG8_BAR __builtin_amdgcn_s_barrier()
; #define tid tid_of(wave)
; template <class Epi, class Sched, bool ALIGN_EPI = false, bool SP2 = false>
; __device__ __forceinline__ void gemm_phase(PG8_LAS unsigned char* lds, const Gemm g, const Sched& S, const Epi& E, const int wave_) {
;     ...
;     for (int i = 0; i < 2; ++i) { int R, C; stage_rc(tid * 16 + i * 8192, R, C); const int Rb = Epi::PERM ? ((R & ~31) + perm32(R & 31)) : R;
;         voffA[i] = (unsigned)(R * K + C) * 2u; voffB[i] = (unsigned)(Rb * K + C) * 2u; }
;     const size_t kstep = (size_t)(BK * 2);
;     const size_t hstep = (size_t)HALF * K * 2;
;     const size_t tstep = 2 * hstep;
;     const unsigned ldsw = (unsigned)wid * 1024u;
;     const int aoff = lds_byte(wr * 64 + fr, fq * 8), boff = lds_byte(wc * 32 + fr, fq * 8);
;     ...
;     Unit cur, nxt; int ui = 0;
;     if (!S.next(0, cur)) return;
;     f32x4 acc[2][2][4][2];
; #pragma unroll
;     for (int a = 0; a < 2; ++a)
; #pragma unroll
;         for (int b = 0; b < 2; ++b)
; #pragma unroll
;             for (int m = 0; m < 4; ++m)
; #pragma unroll
;                 for (int n = 0; n < 2; ++n) acc[a][b][m][n] = (f32x4){0.f, 0.f, 0.f, 0.f};
;     bf16x8 At[4][2], B0[2][2], B1[2][2];
;     const char* cA = (const char*)g.A + (size_t)cur.pm * tstep; const char* cB = (const char*)g.Bt + (size_t)cur.pn * tstep;
;     S.a_ready(cur);
;     if constexpr (SP2) {
;         PG8_STAGE(PG8_SB(0, 0), cB, voffB); PG8_STAGE(PG8_SB(0, 1), cB + hstep, voffB); PG8_STAGE(PG8_SA(0, 0), cA, voffA); PG8_STAGE(PG8_SA(0, 1), cA + hstep, voffA);
;         if (wr == 1) PG8_BAR;
.LBB0_389:
	s_andn2_b64 vcc, exec, s[0:1]
	s_cbranch_vccnz .LBB0_425
	v_readlane_b32 s100, v248, 35
	s_cmpk_lg_i32 s100, 0x100
	s_cbranch_scc1 .Lp3_nowait
	v_readlane_b32 s100, v248, 0
	s_cmp_gt_i32 s100, 2
	s_cbranch_scc1 .Lp3_nowait
	s_cmp_gt_u32 s67, 63
	s_cbranch_scc1 .Lp3_meet
	s_lshl_b32 s98, s26, 8
	s_add_i32 s98, s98, 12
	v_mov_b32_e32 v236, s98
	s_add_u32 s98, s82, 0x310000
	s_addc_u32 s99, s83, 0
	s_mov_b32 s100, 0
.Lp3_poll:
	global_load_dword v237, v236, s[98:99] sc1
	s_waitcnt vmcnt(0)
	v_readfirstlane_b32 s101, v237
	s_cmpk_ge_u32 s101, 0x100
	s_cbranch_scc1 .Lp3_meet
	s_add_i32 s100, s100, 1
	s_cmp_lt_u32 s100, 0x10000
	s_cbranch_scc0 .Lp3_meet
	s_sleep 2
	s_branch .Lp3_poll
.Lp3_meet:
	s_barrier
.Lp3_nowait:
	v_readlane_b32 s1, v248, 22
	s_lshl_b32 s36, s1, 10
	v_lshl_add_u32 v0, v195, 4, s36
	v_ashrrev_i32_e32 v1, 31, v0
	v_lshrrev_b32_e32 v1, 22, v1
	v_add_u32_e32 v1, v0, v1
	v_ashrrev_i32_e32 v8, 10, v1
	v_mul_i32_i24_e32 v1, 0x400, v8
	v_sub_u32_e32 v1, v0, v1
	v_lshrrev_b32_e32 v2, 4, v1
	v_bitop3_b32 v1, v2, v1, 32 bitop3:0x6c
	v_ashrrev_i32_e32 v3, 31, v1
	v_lshrrev_b32_e32 v3, 26, v3
	v_add_u32_e32 v3, v1, v3
	v_lshlrev_b32_e32 v2, 3, v8
	v_ashrrev_i32_e32 v9, 6, v3
	v_and_b32_e32 v3, 0xc0, v3
	v_and_b32_e32 v2, -16, v2
	v_sub_u32_e32 v1, v1, v3
	v_mov_b32_e32 v3, 1
	v_add_u32_e32 v2, v9, v2
	v_ashrrev_i16_sdwa v1, v3, sext(v1) dst_sel:DWORD dst_unused:UNUSED_PAD src0_sel:DWORD src1_sel:BYTE_0
	v_lshlrev_b32_e32 v4, 5, v8
	v_bfe_i32 v10, v1, 0, 16
	v_lshlrev_b32_e32 v1, 1, v2
	v_lshrrev_b32_e32 v5, 2, v2
	v_and_b32_e32 v6, 3, v9
	s_mov_b32 s1, 0x7ffe0
	v_and_b32_e32 v4, 32, v4
	v_and_b32_e32 v1, 24, v1
	v_and_b32_e32 v5, 4, v5
	v_and_or_b32 v6, v2, s1, v6
	v_or3_b32 v1, v6, v5, v1
	v_add_lshl_u32 v4, v4, v10, 1
	v_add_u32_e32 v0, 0x2000, v0
	v_lshl_add_u32 v156, v1, 13, v4
	v_ashrrev_i32_e32 v1, 31, v0
	v_lshrrev_b32_e32 v1, 22, v1
	v_add_u32_e32 v1, v0, v1
	v_ashrrev_i32_e32 v11, 10, v1
	v_mul_i32_i24_e32 v1, 0x400, v11
	v_sub_u32_e32 v0, v0, v1
	v_lshrrev_b32_e32 v1, 4, v0
	v_bitop3_b32 v0, v1, v0, 32 bitop3:0x6c
	v_lshl_add_u32 v154, v2, 13, v4
	v_ashrrev_i32_e32 v2, 31, v0
	v_lshrrev_b32_e32 v2, 26, v2
	v_add_u32_e32 v2, v0, v2
	v_ashrrev_i32_e32 v12, 6, v2
	v_and_b32_e32 v2, 0xffc0, v2
	s_lshr_b32 s0, s67, 8
	v_sub_u32_e32 v0, v0, v2
	v_lshrrev_b16_e32 v2, 7, v0
	s_cmp_eq_u32 s0, 1
	v_lshlrev_b32_e32 v1, 3, v11
	v_and_b32_e32 v2, 1, v2
	s_cselect_b64 s[10:11], -1, 0
	s_ashr_i32 s27, s26, 31
	s_ashr_i32 s25, s24, 31
	v_and_b32_e32 v1, -16, v1
	v_add_u16_e32 v0, v0, v2
	s_lshl_b64 s[4:5], s[26:27], 21
	s_lshl_b64 s[12:13], s[24:25], 21
	v_readlane_b32 s14, v248, 29
	v_add_u32_e32 v1, v12, v1
	v_ashrrev_i16_sdwa v0, v3, sext(v0) dst_sel:DWORD dst_unused:UNUSED_PAD src0_sel:DWORD src1_sel:BYTE_0
	v_readlane_b32 s15, v248, 30
	s_add_u32 s30, s14, s12
	v_lshlrev_b32_e32 v4, 5, v11
	v_bfe_i32 v13, v0, 0, 16
	v_lshlrev_b32_e32 v0, 1, v1
	v_lshrrev_b32_e32 v2, 2, v1
	v_and_b32_e32 v3, 3, v12
	s_addc_u32 s31, s15, s13
	s_add_i32 s27, s36, 0
	v_and_b32_e32 v4, 32, v4
	v_and_b32_e32 v0, 24, v0
	v_and_b32_e32 v2, 4, v2
	v_and_or_b32 v3, v1, s1, v3
	s_add_i32 m0, s27, 0x10000
	s_add_i32 s1, s27, 0x12000
	v_or3_b32 v0, v3, v2, v0
	v_add_lshl_u32 v2, v4, v13, 1
	s_add_u32 s12, s30, 0x100000
	v_lshl_add_u32 v160, v0, 13, v2
	s_addc_u32 s13, s31, 0
	s_add_i32 s14, s27, 0x14000
	s_add_i32 s15, s27, 0x16000
	v_readlane_b32 s16, v248, 25
	global_load_lds_dwordx4 v156, s[30:31]
	s_mov_b32 m0, s1
	v_readlane_b32 s17, v248, 26
	s_add_u32 s28, s16, s4
	global_load_lds_dwordx4 v160, s[30:31]
	s_mov_b32 m0, s14
	s_addc_u32 s29, s17, s5
	s_add_i32 s37, s27, 0x2000
	global_load_lds_dwordx4 v156, s[12:13]
	s_mov_b32 m0, s15
	s_add_u32 s4, s28, 0x100000
	global_load_lds_dwordx4 v160, s[12:13]
	s_mov_b32 m0, s27
	v_lshl_add_u32 v158, v1, 13, v2
	s_addc_u32 s5, s29, 0
	s_add_i32 s40, s27, 0x4000
	global_load_lds_dwordx4 v154, s[28:29]
	s_mov_b32 m0, s37
	s_add_i32 s41, s27, 0x6000
	global_load_lds_dwordx4 v158, s[28:29]
	s_mov_b32 m0, s40
	v_mov_b32_e32 v157, 0
	global_load_lds_dwordx4 v154, s[4:5]
	s_mov_b32 m0, s41
	v_mov_b32_e32 v161, v157
	global_load_lds_dwordx4 v158, s[4:5]
	v_mov_b32_e32 v155, v157
	v_mov_b32_e32 v159, v157
	s_mov_b32 s42, 0
	s_cmp_lg_u32 s0, 1
	v_lshl_add_u64 v[6:7], s[30:31], 0, v[156:157]
	v_lshl_add_u64 v[4:5], s[30:31], 0, v[160:161]
	v_lshl_add_u64 v[2:3], s[28:29], 0, v[154:155]
	v_lshl_add_u64 v[0:1], s[28:29], 0, v[158:159]
	s_cbranch_scc1 .LBB0_392
	s_barrier

; #define PG8_STAGE(bufoff, gbase, voff) do { _Pragma("unroll") for (int _i = 0; _i < 2; ++_i) \
;         __builtin_amdgcn_global_load_lds((const unsigned*)((const char*)(gbase) + (voff)[_i]), (PG8_LAS unsigned*)(lds + (bufoff) + ldsw + _i * 8192), 16, 0, 0); } while (0)
; #define PG8_BAR __builtin_amdgcn_s_barrier()
; #define tid tid_of(wave)
; template <class Epi, class Sched, bool ALIGN_EPI = false, bool SP2 = false>
; __device__ __forceinline__ void gemm_phase(PG8_LAS unsigned char* lds, const Gemm g, const Sched& S, const Epi& E, const int wave_) {
;     ...
;     for (int i = 0; i < 2; ++i) { int R, C; stage_rc(tid * 16 + i * 8192, R, C); const int Rb = Epi::PERM ? ((R & ~31) + perm32(R & 31)) : R;
;         voffA[i] = (unsigned)(R * K + C) * 2u; voffB[i] = (unsigned)(Rb * K + C) * 2u; }
;     const size_t kstep = (size_t)(BK * 2);
;     const size_t hstep = (size_t)HALF * K * 2;
;     const size_t tstep = 2 * hstep;
;     const unsigned ldsw = (unsigned)wid * 1024u;
;     const int aoff = lds_byte(wr * 64 + fr, fq * 8), boff = lds_byte(wc * 32 + fr, fq * 8);
;     ...
;     Unit cur, nxt; int ui = 0;
;     if (!S.next(0, cur)) return;
;     f32x4 acc[2][2][4][2];
; #pragma unroll
;     for (int a = 0; a < 2; ++a)
; #pragma unroll
;         for (int b = 0; b < 2; ++b)
; #pragma unroll
;             for (int m = 0; m < 4; ++m)
; #pragma unroll
;                 for (int n = 0; n < 2; ++n) acc[a][b][m][n] = (f32x4){0.f, 0.f, 0.f, 0.f};
;     bf16x8 At[4][2], B0[2][2], B1[2][2];
;     const char* cA = (const char*)g.A + (size_t)cur.pm * tstep; const char* cB = (const char*)g.Bt + (size_t)cur.pn * tstep;
;     S.a_ready(cur);
;     if constexpr (SP2) {
;         PG8_STAGE(PG8_SB(0, 0), cB, voffB); PG8_STAGE(PG8_SB(0, 1), cB + hstep, voffB); PG8_STAGE(PG8_SA(0, 0), cA, voffA); PG8_STAGE(PG8_SA(0, 1), cA + hstep, voffA);
;         if (wr == 1) PG8_BAR;
.LBB0_482:
	s_andn2_b64 vcc, exec, s[0:1]
	s_cbranch_vccnz .LBB0_534
	v_readlane_b32 s100, v248, 35
	s_cmpk_lg_i32 s100, 0x100
	s_cbranch_scc1 .Lp4_nowait
	v_readlane_b32 s100, v248, 0
	s_cmp_gt_i32 s100, 3
	s_cbranch_scc1 .Lp4_nowait
	s_cmp_gt_u32 s67, 63
	s_cbranch_scc1 .Lp4_meet
	s_lshl_b32 s98, s4, 8
	s_add_i32 s98, s98, 8
	v_mov_b32_e32 v236, s98
	s_add_u32 s98, s82, 0x310000
	s_addc_u32 s99, s83, 0
	s_mov_b32 s100, 0
.Lp4_poll:
	global_load_dword v237, v236, s[98:99] sc1
	s_waitcnt vmcnt(0)
	v_readfirstlane_b32 s101, v237
	s_cmpk_ge_u32 s101, 0x40
	s_cbranch_scc1 .Lp4_meet
	s_add_i32 s100, s100, 1
	s_cmp_lt_u32 s100, 0x10000
	s_cbranch_scc0 .Lp4_meet
	s_sleep 2
	s_branch .Lp4_poll
.Lp4_meet:
	s_barrier
.Lp4_nowait:
	s_lshr_b32 s98, s6, 2
	s_add_i32 s99, s6, s98
	s_and_b32 s99, s99, 3
	s_lshl_b32 s99, s99, 3
	s_and_b32 s98, s98, 3
	s_add_i32 s99, s99, s98
	s_lshr_b32 s98, s6, 4
	s_lshl_b32 s98, s98, 2
	s_add_i32 s6, s99, s98
	v_readlane_b32 s1, v248, 22
	s_lshl_b32 s44, s1, 10
	v_lshl_add_u32 v0, v195, 4, s44
	s_waitcnt lgkmcnt(0)
	v_ashrrev_i32_e32 v1, 31, v0
	v_lshrrev_b32_e32 v1, 22, v1
	v_add_u32_e32 v1, v0, v1
	v_ashrrev_i32_e32 v8, 10, v1
	v_mul_i32_i24_e32 v1, 0x400, v8
	v_sub_u32_e32 v1, v0, v1
	v_lshrrev_b32_e32 v2, 4, v1
	v_bitop3_b32 v1, v2, v1, 32 bitop3:0x6c
	v_ashrrev_i32_e32 v3, 31, v1
	v_lshrrev_b32_e32 v3, 26, v3
	v_add_u32_e32 v3, v1, v3
	v_lshlrev_b32_e32 v2, 3, v8
	v_ashrrev_i32_e32 v9, 6, v3
	v_and_b32_e32 v3, 0xc0, v3
	v_and_b32_e32 v2, -16, v2
	v_sub_u32_e32 v1, v1, v3
	v_mov_b32_e32 v3, 1
	v_add_u32_e32 v2, v9, v2
	v_ashrrev_i16_sdwa v1, v3, sext(v1) dst_sel:DWORD dst_unused:UNUSED_PAD src0_sel:DWORD src1_sel:BYTE_0
	v_lshlrev_b32_e32 v4, 5, v8
	v_bfe_i32 v10, v1, 0, 16
	v_lshlrev_b32_e32 v1, 1, v2
	v_lshrrev_b32_e32 v5, 2, v2
	v_and_b32_e32 v6, 3, v9
	s_mov_b32 s1, 0xfffe0
	v_and_b32_e32 v4, 32, v4
	v_and_b32_e32 v1, 24, v1
	v_and_b32_e32 v5, 4, v5
	v_and_or_b32 v6, v2, s1, v6
	v_or3_b32 v1, v6, v5, v1
	v_add_lshl_u32 v4, v4, v10, 1
	v_add_u32_e32 v0, 0x2000, v0
	v_lshl_add_u32 v130, v1, 12, v4
	v_ashrrev_i32_e32 v1, 31, v0
	v_lshrrev_b32_e32 v1, 22, v1
	v_add_u32_e32 v1, v0, v1
	v_ashrrev_i32_e32 v11, 10, v1
	v_mul_i32_i24_e32 v1, 0x400, v11
	v_sub_u32_e32 v0, v0, v1
	v_lshrrev_b32_e32 v1, 4, v0
	v_bitop3_b32 v0, v1, v0, 32 bitop3:0x6c
	v_lshl_add_u32 v128, v2, 12, v4
	v_ashrrev_i32_e32 v2, 31, v0
	v_lshrrev_b32_e32 v2, 26, v2
	v_add_u32_e32 v2, v0, v2
	v_ashrrev_i32_e32 v12, 6, v2
	v_and_b32_e32 v2, 0xffc0, v2
	s_lshr_b32 s0, s67, 8
	v_sub_u32_e32 v0, v0, v2
	v_lshrrev_b16_e32 v2, 7, v0
	s_cmp_eq_u32 s0, 1
	v_lshlrev_b32_e32 v1, 3, v11
	v_and_b32_e32 v2, 1, v2
	s_cselect_b64 s[12:13], -1, 0
	s_ashr_i32 s5, s4, 31
	s_ashr_i32 s7, s6, 31
	v_and_b32_e32 v1, -16, v1
	v_add_u16_e32 v0, v0, v2
	s_lshl_b64 s[14:15], s[4:5], 20
	s_lshl_b64 s[16:17], s[6:7], 20
	v_readlane_b32 s18, v248, 31
	v_add_u32_e32 v1, v12, v1
	v_ashrrev_i16_sdwa v0, v3, sext(v0) dst_sel:DWORD dst_unused:UNUSED_PAD src0_sel:DWORD src1_sel:BYTE_0
	v_readlane_b32 s19, v248, 32
	s_add_u32 s40, s18, s16
	v_lshlrev_b32_e32 v4, 5, v11
	v_bfe_i32 v13, v0, 0, 16
	v_lshlrev_b32_e32 v0, 1, v1
	v_lshrrev_b32_e32 v2, 2, v1
	v_and_b32_e32 v3, 3, v12
	s_addc_u32 s41, s19, s17
	s_add_i32 s45, s44, 0
	v_and_b32_e32 v4, 32, v4
	v_and_b32_e32 v0, 24, v0
	v_and_b32_e32 v2, 4, v2
	v_and_or_b32 v3, v1, s1, v3
	s_add_i32 m0, s45, 0x10000
	s_add_i32 s1, s45, 0x12000
	v_or3_b32 v0, v3, v2, v0
	v_add_lshl_u32 v2, v4, v13, 1
	s_add_u32 s16, s40, 0x80000
	v_lshl_add_u32 v134, v0, 12, v2
	s_addc_u32 s17, s41, 0
	s_add_i32 s5, s45, 0x14000
	s_add_i32 s7, s45, 0x16000
	global_load_lds_dwordx4 v130, s[40:41]
	s_mov_b32 m0, s1
	s_add_u32 s36, s38, s14
	global_load_lds_dwordx4 v134, s[40:41]
	s_mov_b32 m0, s5
	s_addc_u32 s37, s39, s15
	s_add_i32 s46, s45, 0x2000
	global_load_lds_dwordx4 v130, s[16:17]
	s_mov_b32 m0, s7
	s_add_u32 s14, s36, 0x80000
	global_load_lds_dwordx4 v134, s[16:17]
	s_mov_b32 m0, s45
	v_lshl_add_u32 v132, v1, 12, v2
	s_addc_u32 s15, s37, 0
	s_add_i32 s47, s45, 0x4000
	global_load_lds_dwordx4 v128, s[36:37]
	s_mov_b32 m0, s46
	s_add_i32 s48, s45, 0x6000
	global_load_lds_dwordx4 v132, s[36:37]
	s_mov_b32 m0, s47
	v_mov_b32_e32 v137, 0
	global_load_lds_dwordx4 v128, s[14:15]
	s_mov_b32 m0, s48
	v_mov_b32_e32 v131, v137
	global_load_lds_dwordx4 v132, s[14:15]
	v_mov_b32_e32 v135, v137
	v_mov_b32_e32 v129, v137
	v_mov_b32_e32 v133, v137
	s_mov_b32 s49, 0
	s_mov_b64 s[14:15], 0x80000
	s_cmp_lg_u32 s0, 1
	v_lshl_add_u64 v[6:7], s[40:41], 0, v[130:131]
	v_lshl_add_u64 v[4:5], s[40:41], 0, v[134:135]
	v_lshl_add_u64 v[2:3], s[36:37], 0, v[128:129]
	v_lshl_add_u64 v[0:1], s[36:37], 0, v[132:133]
	s_cbranch_scc1 .LBB0_485
	s_barrier

; #define PG8_STAGE(bufoff, gbase, voff) do { _Pragma("unroll") for (int _i = 0; _i < 2; ++_i) \
;         __builtin_amdgcn_global_load_lds((const unsigned*)((const char*)(gbase) + (voff)[_i]), (PG8_LAS unsigned*)(lds + (bufoff) + ldsw + _i * 8192), 16, 0, 0); } while (0)
; #define PG8_BAR __builtin_amdgcn_s_barrier()
; #define tid tid_of(wave)
; template <class Epi, class Sched, bool ALIGN_EPI = false, bool SP2 = false>
; __device__ __forceinline__ void gemm_phase(PG8_LAS unsigned char* lds, const Gemm g, const Sched& S, const Epi& E, const int wave_) {
;     ...
;     for (int i = 0; i < 2; ++i) { int R, C; stage_rc(tid * 16 + i * 8192, R, C); const int Rb = Epi::PERM ? ((R & ~31) + perm32(R & 31)) : R;
;         voffA[i] = (unsigned)(R * K + C) * 2u; voffB[i] = (unsigned)(Rb * K + C) * 2u; }
;     const size_t kstep = (size_t)(BK * 2);
;     const size_t hstep = (size_t)HALF * K * 2;
;     const size_t tstep = 2 * hstep;
;     const unsigned ldsw = (unsigned)wid * 1024u;
;     const int aoff = lds_byte(wr * 64 + fr, fq * 8), boff = lds_byte(wc * 32 + fr, fq * 8);
;     ...
;     Unit cur, nxt; int ui = 0;
;     if (!S.next(0, cur)) return;
;     f32x4 acc[2][2][4][2];
; #pragma unroll
;     for (int a = 0; a < 2; ++a)
; #pragma unroll
;         for (int b = 0; b < 2; ++b)
; #pragma unroll
;             for (int m = 0; m < 4; ++m)
; #pragma unroll
;                 for (int n = 0; n < 2; ++n) acc[a][b][m][n] = (f32x4){0.f, 0.f, 0.f, 0.f};
;     bf16x8 At[4][2], B0[2][2], B1[2][2];
;     const char* cA = (const char*)g.A + (size_t)cur.pm * tstep; const char* cB = (const char*)g.Bt + (size_t)cur.pn * tstep;
;     S.a_ready(cur);
;     if constexpr (SP2) {
;         PG8_STAGE(PG8_SB(0, 0), cB, voffB); PG8_STAGE(PG8_SB(0, 1), cB + hstep, voffB); PG8_STAGE(PG8_SA(0, 0), cA, voffA); PG8_STAGE(PG8_SA(0, 1), cA + hstep, voffA);
;         if (wr == 1) PG8_BAR;
.LBB0_687:
	s_andn2_b64 vcc, exec, s[0:1]
	s_cbranch_vccnz .LBB0_742
	s_cmpk_lg_i32 s88, 0x100
	s_cbranch_scc1 .Lp6_nowait
	v_readlane_b32 s100, v248, 0
	s_cmp_gt_i32 s100, 5
	s_cbranch_scc1 .Lp6_nowait
	s_cmp_gt_u32 s67, 63
	s_cbranch_scc1 .Lp6_meet
	s_lshl_b32 s98, s28, 8
	s_add_i32 s98, s98, 4
	v_mov_b32_e32 v236, s98
	s_add_u32 s98, s82, 0x310000
	s_addc_u32 s99, s83, 0
	s_mov_b32 s100, 0
.Lp6_poll:
	global_load_dword v237, v236, s[98:99] sc1
	s_waitcnt vmcnt(0)
	v_readfirstlane_b32 s101, v237
	s_cmpk_ge_u32 s101, 0x80
	s_cbranch_scc1 .Lp6_meet
	s_add_i32 s100, s100, 1
	s_cmp_lt_u32 s100, 0x10000
	s_cbranch_scc0 .Lp6_meet
	s_sleep 2
	s_branch .Lp6_poll
.Lp6_ready:
.Lp6_meet:
	s_barrier
.Lp6_nowait:
	v_readlane_b32 s1, v248, 22
	s_lshl_b32 s2, s1, 10
	v_lshl_add_u32 v0, v195, 4, s2
	s_waitcnt lgkmcnt(0)
	v_ashrrev_i32_e32 v1, 31, v0
	v_lshrrev_b32_e32 v1, 22, v1
	v_add_u32_e32 v1, v0, v1
	v_ashrrev_i32_e32 v8, 10, v1
	v_mul_i32_i24_e32 v1, 0x400, v8
	v_sub_u32_e32 v1, v0, v1
	v_lshrrev_b32_e32 v2, 4, v1
	v_bitop3_b32 v1, v2, v1, 32 bitop3:0x6c
	v_ashrrev_i32_e32 v3, 31, v1
	v_lshrrev_b32_e32 v3, 26, v3
	v_add_u32_e32 v3, v1, v3
	v_lshlrev_b32_e32 v2, 3, v8
	v_ashrrev_i32_e32 v9, 6, v3
	v_and_b32_e32 v3, 0xc0, v3
	v_and_b32_e32 v2, -16, v2
	v_sub_u32_e32 v1, v1, v3
	v_mov_b32_e32 v3, 1
	v_add_u32_e32 v2, v9, v2
	v_ashrrev_i16_sdwa v1, v3, sext(v1) dst_sel:DWORD dst_unused:UNUSED_PAD src0_sel:DWORD src1_sel:BYTE_0
	v_lshlrev_b32_e32 v4, 5, v8
	v_bfe_i32 v10, v1, 0, 16
	v_lshlrev_b32_e32 v1, 1, v2
	v_lshrrev_b32_e32 v5, 2, v2
	v_and_b32_e32 v6, 3, v9
	s_mov_b32 s1, 0xfffe0
	v_and_b32_e32 v4, 32, v4
	v_and_b32_e32 v1, 24, v1
	v_and_b32_e32 v5, 4, v5
	v_and_or_b32 v6, v2, s1, v6
	v_or3_b32 v1, v6, v5, v1
	v_add_lshl_u32 v4, v4, v10, 1
	v_add_u32_e32 v0, 0x2000, v0
	v_lshl_add_u32 v146, v1, 12, v4
	v_ashrrev_i32_e32 v1, 31, v0
	v_lshrrev_b32_e32 v1, 22, v1
	v_add_u32_e32 v1, v0, v1
	v_ashrrev_i32_e32 v11, 10, v1
	v_mul_i32_i24_e32 v1, 0x400, v11
	v_sub_u32_e32 v0, v0, v1
	v_lshrrev_b32_e32 v1, 4, v0
	v_bitop3_b32 v0, v1, v0, 32 bitop3:0x6c
	v_lshl_add_u32 v144, v2, 12, v4
	v_ashrrev_i32_e32 v2, 31, v0
	v_lshrrev_b32_e32 v2, 26, v2
	v_add_u32_e32 v2, v0, v2
	v_ashrrev_i32_e32 v12, 6, v2
	v_and_b32_e32 v2, 0xffc0, v2
	s_lshr_b32 s0, s67, 8
	v_sub_u32_e32 v0, v0, v2
	v_lshrrev_b16_e32 v2, 7, v0
	s_cmp_eq_u32 s0, 1
	v_lshlrev_b32_e32 v1, 3, v11
	v_and_b32_e32 v2, 1, v2
	s_cselect_b64 s[10:11], -1, 0
	s_ashr_i32 s29, s28, 31
	s_ashr_i32 s31, s30, 31
	v_and_b32_e32 v1, -16, v1
	v_add_u16_e32 v0, v0, v2
	s_lshl_b64 s[4:5], s[28:29], 20
	s_lshl_b64 s[6:7], s[30:31], 20
	v_add_u32_e32 v1, v12, v1
	v_ashrrev_i16_sdwa v0, v3, sext(v0) dst_sel:DWORD dst_unused:UNUSED_PAD src0_sel:DWORD src1_sel:BYTE_0
	s_add_u32 s36, s62, s6
	v_lshlrev_b32_e32 v4, 5, v11
	v_bfe_i32 v13, v0, 0, 16
	v_lshlrev_b32_e32 v0, 1, v1
	v_lshrrev_b32_e32 v2, 2, v1
	v_and_b32_e32 v3, 3, v12
	s_addc_u32 s37, s63, s7
	s_add_i32 s42, s2, 0
	v_and_b32_e32 v4, 32, v4
	v_and_b32_e32 v0, 24, v0
	v_and_b32_e32 v2, 4, v2
	v_and_or_b32 v3, v1, s1, v3
	s_add_i32 m0, s42, 0x10000
	s_add_i32 s1, s42, 0x12000
	v_or3_b32 v0, v3, v2, v0
	v_add_lshl_u32 v2, v4, v13, 1
	s_add_u32 s6, s36, 0x80000
	v_lshl_add_u32 v150, v0, 12, v2
	s_addc_u32 s7, s37, 0
	s_add_i32 s12, s42, 0x14000
	s_add_i32 s13, s42, 0x16000
	v_readlane_b32 s14, v248, 25
	global_load_lds_dwordx4 v146, s[36:37]
	s_mov_b32 m0, s1
	v_readlane_b32 s15, v248, 26
	s_add_u32 s34, s14, s4
	global_load_lds_dwordx4 v150, s[36:37]
	s_mov_b32 m0, s12
	s_addc_u32 s35, s15, s5
	s_add_i32 s43, s42, 0x2000
	global_load_lds_dwordx4 v146, s[6:7]
	s_mov_b32 m0, s13
	s_add_u32 s4, s34, 0x80000
	global_load_lds_dwordx4 v150, s[6:7]
	s_mov_b32 m0, s42
	v_lshl_add_u32 v148, v1, 12, v2
	s_addc_u32 s5, s35, 0
	s_add_i32 s44, s42, 0x4000
	global_load_lds_dwordx4 v144, s[34:35]
	s_mov_b32 m0, s43
	s_add_i32 s45, s42, 0x6000
	global_load_lds_dwordx4 v148, s[34:35]
	s_mov_b32 m0, s44
	v_mov_b32_e32 v147, 0
	global_load_lds_dwordx4 v144, s[4:5]
	s_mov_b32 m0, s45
	v_mov_b32_e32 v151, v147
	global_load_lds_dwordx4 v148, s[4:5]
	v_mov_b32_e32 v145, v147
	v_mov_b32_e32 v149, v147
	s_mov_b32 s46, 0
	s_cmp_lg_u32 s0, 1
	v_lshl_add_u64 v[6:7], s[36:37], 0, v[146:147]
	v_lshl_add_u64 v[4:5], s[36:37], 0, v[150:151]
	v_lshl_add_u64 v[2:3], s[34:35], 0, v[144:145]
	v_lshl_add_u64 v[0:1], s[34:35], 0, v[148:149]
	s_cbranch_scc1 .LBB0_690
	s_barrier
